# attention softmax: compiler-packed v_pk_fma_f32 score scalings split into plain v_fma_f32 pairs
# baseline (speedup 1.0000x reference)
; __device__ __forceinline__ void partialSM(f32x16& p0, f32x16& p1, float& m_reg, float& mn, float& alpha) {
;     float pmax;
;     {
;     ...
;       float a = MX3_(p0[0], p0[1], p1[0]), b = MX3_(p0[2], p0[3], p1[1]); a = MX3_(a, p1[2], p1[3]);
; #pragma unroll
;       for (int r = 4; r < 16; r += 4) { a = MX3_(a, p0[r], p0[r + 1]); b = MX3_(b, p0[r + 2], p0[r + 3]); a = MX3_(a, p1[r], p1[r + 1]); b = MX3_(b, p1[r + 2], p1[r + 3]); }
;       pmax = __builtin_fmaxf(a, b);
;     ...
;     }
;     { auto rr = __builtin_amdgcn_permlane32_swap(__float_as_uint(pmax), __float_as_uint(pmax), false, false);
;       pmax = fmaxf(__uint_as_float(rr[0]), __uint_as_float(rr[1])); }
;     constexpr float C2 = 1.4426950408889634f * SCALE;
;     if (__builtin_expect(__all((pmax - m_reg) * SCALE <= THR), 1)) { mn = m_reg; alpha = 1.f; }
;     else { mn = fmaxf(m_reg, pmax); alpha = __builtin_amdgcn_exp2f((m_reg - mn) * C2); m_reg = mn; }
;     const float mnL = -mn * C2;
;     for (int r = 0; r < 16; ++r) p0[r] = fmaf(p0[r], C2, mnL); for (int r = 0; r < 16; ++r) p1[r] = fmaf(p1[r], C2, mnL);
;     for (int r = 0; r < 16; ++r) p0[r] = __builtin_amdgcn_exp2f(p0[r]);
; __device__ __forceinline__ void block(const BlockRef& cur, const BlockRef& nxt, int skv, char* lds, Seam& S) {
;     ...
;     int j_hi = (cur.P0 + QB - 1) / KVBLK + 1; if (j_hi > skv / KVBLK) j_hi = skv / KVBLK;
;     const int NT = j_hi - j_lo;
;     const int kbn = 0;
;     const int qlo = cur.P0 + wid * QBLK, qm = qlo + r32 - 4 * hi;
;     char* V_lds = lds; char* K_lds = lds + 2 * SHM_V;
;     float* ws = (float*)(lds + 2 * SHM_V + 2 * SHM_K) + wid * 64; float* li_l = ws, * al_l = ws + 32;
;     float m_reg = -1e30f, l_reg = 0; f32x16 o[4] = {};
;     const int sr = tid >> 4, sc = (tid & 15) * 8, vst0 = v_st(sr, sc), vst1 = v_st(32 + sr, sc), kws = KSWZ(sr, sc * 2);
;     const int vb0 = (int)(uintptr_t)V_lds + v_rd_base(lane);
;     const bf16* Kh = cur.K; const bf16* Vh = cur.V;
;     ...
;     constexpr int NQL = 8;
;     constexpr bool SK = false;
;     ...
;     f32x16 pA0, pA1, pB0, pB1; float mnA, mnB, alA, alB; bf16x8 pa0, pa1, pa2, pa3;
;     SWRITE_HV(0); SBAR();
;     if (NT > 1) { SLOAD_H(Kh, Vh, KBASE(1)); }
;     SBAR(); qkt<0, SK>(pA0, pA1, K_lds, r32, hi, S.qr, ACT(0));
;     MASKT(pA0, pA1, 0); partialSM(pA0, pA1, m_reg, mnA, alA);
;     if (NT > 1) { VMW(); SWRITE_HK(1); }
;     __syncthreads();
.LBB0_382:
	s_nop 8
	v_max_f32_e32 v2, v21, v21
	v_max_f32_e32 v44, v20, v20
	v_max_f32_e32 v2, v44, v2
	v_max3_f32 v44, v22, v23, v5
	v_max3_f32 v2, v2, v4, v6
	v_max3_f32 v2, v2, v7, v24
	v_max3_f32 v44, v44, v26, v27
	v_max3_f32 v2, v2, v25, v8
	v_max3_f32 v44, v44, v10, v11
	v_max3_f32 v2, v2, v9, v28
	v_max3_f32 v44, v44, v30, v31
	v_max3_f32 v2, v2, v29, v12
	v_max3_f32 v44, v44, v14, v15
	v_max3_f32 v2, v2, v13, v32
	v_max3_f32 v44, v44, v34, v35
	v_max3_f32 v2, v2, v33, v16
	v_max3_f32 v44, v44, v18, v19
	v_max3_f32 v2, v2, v17, v44
	s_add_i32 s7, s59, 0xff
	v_mov_b32_e32 v44, v2
	s_lshr_b32 s7, s7, 6
	s_nop 0
	v_permlane32_swap_b32_e32 v2, v44
	s_add_i32 s7, s7, 1
	v_max_f32_e32 v44, v44, v44
	v_max_f32_e32 v2, v2, v2
	s_cmpk_lt_i32 s59, 0xf81
	v_max_f32_e32 v2, v2, v44
	s_cselect_b32 s72, s7, 0x42
	s_and_b32 s6, s6, 0x3fffffc0
	v_add_f32_e32 v44, 0x7149f2ca, v2
	s_lshl_b32 s6, s6, 2
	v_mul_f32_e32 v44, 0x3db504f3, v44
	v_max_f32_e32 v2, 0xf149f2ca, v2
	s_add_i32 s6, s6, 0
	v_cmp_ge_f32_e32 vcc, s61, v44
	v_sub_f32_e32 v44, 0xf149f2ca, v2
	s_add_i32 s6, s6, 0x10000
	v_mul_f32_e32 v44, 0x3e0293ee, v44
	v_exp_f32_e32 v44, v44
	s_cmp_eq_u64 vcc, exec
	s_cselect_b64 vcc, -1, 0
	v_cndmask_b32_e32 v188, v2, v230, vcc
	v_mul_f32_e32 v2, 0xbe0293ee, v188
	v_cndmask_b32_e64 v201, v44, 1.0, vcc
	v_mov_b32_e32 v44, v2
	v_fmamk_f32 v20, v20, 0x3e0293ee, v2
	v_fmamk_f32 v21, v21, 0x3e0293ee, v2
	v_fmamk_f32 v22, v22, 0x3e0293ee, v2
	v_fmamk_f32 v23, v23, 0x3e0293ee, v2
	v_fmamk_f32 v24, v24, 0x3e0293ee, v2
	v_fmamk_f32 v25, v25, 0x3e0293ee, v2
	v_fmamk_f32 v26, v26, 0x3e0293ee, v2
	v_fmamk_f32 v27, v27, 0x3e0293ee, v2
	v_fmamk_f32 v28, v28, 0x3e0293ee, v2
	v_fmamk_f32 v29, v29, 0x3e0293ee, v2
	v_fmamk_f32 v30, v30, 0x3e0293ee, v2
	v_fmamk_f32 v31, v31, 0x3e0293ee, v2
	v_fmamk_f32 v32, v32, 0x3e0293ee, v2
	v_fmamk_f32 v33, v33, 0x3e0293ee, v2
	v_fmamk_f32 v34, v34, 0x3e0293ee, v2
	v_fmac_f32_e32 v44, 0x3e0293ee, v35
	v_fma_f32 v174, v16, s38, v2
	v_fma_f32 v175, v17, s38, v2
	v_exp_f32_e32 v129, v20
	v_exp_f32_e32 v131, v21
	v_exp_f32_e32 v128, v22
	v_exp_f32_e32 v130, v23
	v_exp_f32_e32 v125, v24
	v_exp_f32_e32 v127, v25
	v_exp_f32_e32 v124, v26
	v_exp_f32_e32 v126, v27
	v_exp_f32_e32 v121, v28
	v_exp_f32_e32 v123, v29
	v_exp_f32_e32 v120, v30
	v_exp_f32_e32 v122, v31
	v_exp_f32_e32 v117, v32
	v_exp_f32_e32 v119, v33
	v_exp_f32_e32 v116, v34
	v_exp_f32_e32 v118, v44
	v_mov_b32_e32 v16, v3
	v_mov_b32_e32 v17, v3
	v_fma_f32 v172, v18, s38, v2
	v_fma_f32 v173, v19, s38, v2
	v_fma_f32 v176, v14, s38, v2
	v_fma_f32 v177, v15, s38, v2
	v_fma_f32 v178, v12, s38, v2
	v_fma_f32 v179, v13, s38, v2
	v_fma_f32 v180, v10, s38, v2
	v_fma_f32 v181, v11, s38, v2
	v_fma_f32 v182, v8, s38, v2
	v_fma_f32 v183, v9, s38, v2
	v_fma_f32 v184, v6, s38, v2
	v_fma_f32 v185, v7, s38, v2
	v_fma_f32 v186, v4, s38, v2
	v_fma_f32 v187, v5, s38, v2
	s_waitcnt vmcnt(0)
	s_waitcnt vmcnt(1)
	ds_write_b128 v231, v[36:39] offset:49152
	s_waitcnt vmcnt(0)
	ds_write_b128 v231, v[40:43] offset:57344
	v_mov_b32_e32 v2, v3
	v_mov_b32_e32 v4, v3
	v_mov_b32_e32 v5, v3
	v_mov_b32_e32 v6, v3
	v_mov_b32_e32 v7, v3
	v_mov_b32_e32 v8, v3
	v_mov_b32_e32 v9, v3
	v_mov_b32_e32 v10, v3
	v_mov_b32_e32 v11, v3
	v_mov_b32_e32 v12, v3
	v_mov_b32_e32 v13, v3
	v_mov_b32_e32 v14, v3
	v_mov_b32_e32 v15, v3
	v_mov_b64_e32 v[66:67], v[16:17]
	v_mov_b64_e32 v[50:51], v[16:17]
	v_mov_b64_e32 v[34:35], v[16:17]
	v_mov_b64_e32 v[64:65], v[14:15]
	v_mov_b64_e32 v[62:63], v[12:13]
	v_mov_b64_e32 v[60:61], v[10:11]
	v_mov_b64_e32 v[58:59], v[8:9]
	v_mov_b64_e32 v[56:57], v[6:7]
	v_mov_b64_e32 v[54:55], v[4:5]
	v_mov_b64_e32 v[52:53], v[2:3]
	v_mov_b64_e32 v[48:49], v[14:15]
	v_mov_b64_e32 v[46:47], v[12:13]
	v_mov_b64_e32 v[44:45], v[10:11]
	v_mov_b64_e32 v[42:43], v[8:9]
	v_mov_b64_e32 v[40:41], v[6:7]
	v_mov_b64_e32 v[38:39], v[4:5]
	v_mov_b64_e32 v[36:37], v[2:3]
	v_mov_b64_e32 v[32:33], v[14:15]
	v_mov_b64_e32 v[30:31], v[12:13]
	v_mov_b64_e32 v[28:29], v[10:11]
	v_mov_b64_e32 v[26:27], v[8:9]
	v_mov_b64_e32 v[24:25], v[6:7]
	v_mov_b64_e32 v[22:23], v[4:5]
	v_mov_b64_e32 v[20:21], v[2:3]
	v_mov_b64_e32 v[18:19], v[16:17]
	s_mov_b32 s73, 2
	v_lshl_add_u64 v[216:217], s[16:17], 0, v[206:207]
	v_lshl_add_u64 v[218:219], s[12:13], 0, v[206:207]
	v_lshl_add_u32 v209, v198, 2, s6
	v_lshl_add_u32 v205, v199, 2, s6
	v_add_u32_e32 v207, s36, v220
	v_mov_b32_e32 v232, 0
	s_movk_i32 s74, 0x7f
	v_mov_b64_e32 v[16:17], v[14:15]
	v_mov_b64_e32 v[14:15], v[12:13]
	v_mov_b64_e32 v[12:13], v[10:11]
	v_mov_b64_e32 v[10:11], v[8:9]
	v_mov_b64_e32 v[8:9], v[6:7]
	v_mov_b64_e32 v[6:7], v[4:5]
	v_mov_b64_e32 v[4:5], v[2:3]
	s_waitcnt lgkmcnt(0)
	s_barrier

; __device__ __forceinline__ void partialSM(f32x16& p0, f32x16& p1, float& m_reg, float& mn, float& alpha) {
;     ...
;     if (__builtin_expect(__all((pmax - m_reg) * SCALE <= THR), 1)) { mn = m_reg; alpha = 1.f; }
;     else { mn = fmaxf(m_reg, pmax); alpha = __builtin_amdgcn_exp2f((m_reg - mn) * C2); m_reg = mn; }
;     const float mnL = -mn * C2;
;     for (int r = 0; r < 16; ++r) p0[r] = fmaf(p0[r], C2, mnL); for (int r = 0; r < 16; ++r) p1[r] = fmaf(p1[r], C2, mnL);
;     for (int r = 0; r < 16; ++r) p0[r] = __builtin_amdgcn_exp2f(p0[r]);
; __device__ __forceinline__ void block(const BlockRef& cur, const BlockRef& nxt, int skv, char* lds, Seam& S) {
;     ...
;     for (int t = 1; t + 1 < NT; t += 2) {
;         HALF_STEP(pB0, pB1, mnB, alB, pA0, pA1, alA, t, 1, 0, 0);
;         HALF_STEP(pA0, pA1, mnA, alA, pB0, pB1, alB, t + 1, 0, 1, 1);
.LBB0_399:
	s_waitcnt lgkmcnt(0)
	s_barrier
	v_cndmask_b32_e64 v188, v2, v235, s[6:7]
	v_mul_f32_e32 v2, 0xbe0293ee, v188
	v_fmamk_f32 v116, v116, 0x3e0293ee, v2
	v_fmamk_f32 v117, v117, 0x3e0293ee, v2
	v_fmamk_f32 v118, v118, 0x3e0293ee, v2
	v_fmamk_f32 v119, v119, 0x3e0293ee, v2
	v_fmamk_f32 v120, v120, 0x3e0293ee, v2
	v_fmamk_f32 v121, v121, 0x3e0293ee, v2
	v_fmamk_f32 v122, v122, 0x3e0293ee, v2
	v_fmamk_f32 v123, v123, 0x3e0293ee, v2
	v_fmamk_f32 v172, v124, 0x3e0293ee, v2
	v_fmamk_f32 v173, v125, 0x3e0293ee, v2
	v_fmamk_f32 v174, v126, 0x3e0293ee, v2
	v_fmamk_f32 v175, v127, 0x3e0293ee, v2
	s_waitcnt vmcnt(0)
	v_fmamk_f32 v176, v128, 0x3e0293ee, v2
	v_fmamk_f32 v177, v129, 0x3e0293ee, v2
	v_fmamk_f32 v178, v130, 0x3e0293ee, v2
	v_fmamk_f32 v179, v131, 0x3e0293ee, v2
	v_exp_f32_e32 v129, v116
	v_exp_f32_e32 v131, v117
	v_exp_f32_e32 v128, v118
	v_exp_f32_e32 v130, v119
	v_exp_f32_e32 v125, v120
	v_exp_f32_e32 v127, v121
	v_exp_f32_e32 v124, v122
	v_exp_f32_e32 v126, v123
	v_exp_f32_e32 v121, v172
	v_exp_f32_e32 v123, v173
	v_exp_f32_e32 v120, v174
	v_exp_f32_e32 v122, v175
	v_exp_f32_e32 v117, v176
	v_exp_f32_e32 v119, v177
	v_exp_f32_e32 v116, v178
	v_exp_f32_e32 v118, v179
	v_fma_f32 v186, v100, s38, v2
	v_fma_f32 v187, v101, s38, v2
	v_fma_f32 v184, v102, s38, v2
	v_fma_f32 v185, v103, s38, v2
	v_fma_f32 v182, v104, s38, v2
	v_fma_f32 v183, v105, s38, v2
	v_fma_f32 v180, v106, s38, v2
	v_fma_f32 v181, v107, s38, v2
	v_fma_f32 v178, v108, s38, v2
	v_fma_f32 v179, v109, s38, v2
	v_fma_f32 v176, v110, s38, v2
	v_fma_f32 v177, v111, s38, v2
	v_fma_f32 v174, v112, s38, v2
	v_fma_f32 v175, v113, s38, v2
	v_fma_f32 v172, v114, s38, v2
	v_fma_f32 v173, v115, s38, v2
	v_add_f32_e32 v2, v211, v213
	v_fmac_f32_e32 v2, v201, v232
	v_add_f32_e32 v232, v237, v238
	s_addk_i32 s74, 0x80
	s_add_i32 s73, s73, 2
	v_fmac_f32_e32 v232, v2, v233
	s_cmp_ge_u32 s73, s72
	v_add_u32_e32 v207, 0xffffff80, v207
	s_cbranch_scc1 .LBB0_401
	v_mov_b32_e32 v201, v189
	s_branch .LBB0_383
